# GEMM phase prologues: K-tile 1 staging issued before the first wait/barrier instead of after it
# speedup vs baseline: 1.0091x; 1.0008x over previous
; #define PG8_STAGE(bufoff, gbase, voff) do { _Pragma("unroll") for (int _i = 0; _i < 2; ++_i) \
;         __builtin_amdgcn_global_load_lds((const unsigned*)((const char*)(gbase) + (voff)[_i]), (PG8_LAS unsigned*)(lds + (bufoff) + ldsw + _i * 8192), 16, 0, 0); } while (0)
; #define PG8_WAIT_V(n) asm volatile("s_waitcnt vmcnt(" #n ")" ::: "memory")
; #define PG8_BAR __builtin_amdgcn_s_barrier()
; template <class Epi, class Sched, bool ALIGN_EPI = false, bool SP2 = false, bool KSEG = false>
; __device__ __forceinline__ void gemm_phase(PG8_LAS unsigned char* lds, const Gemm g, const Sched& S, const Epi& E) {
;     ...
;     for (int i = 0; i < 2; ++i) { int R, C; stage_rc(tid * 16 + i * 8192, R, C); const int Rb = Epi::PERM ? ((R & ~31) + perm32(R & 31)) : R;
;         voffA[i] = (unsigned)(R * K + C) * 2u; voffB[i] = (unsigned)(Rb * K + C) * 2u; }
;     const size_t kstep = (size_t)(BK * 2);
;     const size_t hstep = (size_t)HALF * K * 2;
;     const size_t tstep = 2 * hstep;
;     const unsigned ldsw = (unsigned)wid * 1024u;
;     const int aoff = lds_byte(wr * 64 + fr, fq * 8), boff = lds_byte(wc * 32 + fr, fq * 8);
;     ...
;         PG8_STAGE(PG8_SB(0, 0), cB, voffB); PG8_STAGE(PG8_SB(0, 1), cB + hstep, voffB); PG8_STAGE(PG8_SA(0, 0), cA, voffA); PG8_STAGE(PG8_SA(0, 1), cA + hstep, voffA);
;         if (wr == 1) PG8_BAR;
;         PG8_WAIT_V(2); PG8_BAR;
;         PG8_STAGE(PG8_SB(1, 0), cB + kstep, voffB); PG8_STAGE(PG8_SA(1, 0), cA + kstep, voffA); PG8_STAGE(PG8_SB(1, 1), cB + hstep + kstep, voffB);
;         PG8_WAIT_V(6); PG8_BAR;
.LBB0_114:
	s_lshl_b32 s12, s12, 5
	s_and_b32 s20, s12, 0x60
	s_mov_b64 s[12:13], 0x80
	s_add_i32 m0, s27, 0x18000
	v_lshl_add_u64 v[8:9], v[8:9], 0, s[12:13]
	s_lshl_b32 s17, s16, 13
	s_lshl_b32 s21, s20, 7
	global_load_lds_dwordx4 v[8:9], off
	v_lshl_add_u64 v[6:7], v[6:7], 0, s[12:13]
	s_add_i32 m0, s27, 0x1a000
	s_add_i32 s51, s27, 0x8000
	s_add_i32 s58, s27, 0xa000
	global_load_lds_dwordx4 v[6:7], off
	v_lshl_add_u64 v[2:3], v[2:3], 0, s[12:13]
	s_mov_b32 m0, s51
	s_add_u32 s18, s30, 0x80080
	global_load_lds_dwordx4 v[2:3], off
	v_lshl_add_u64 v[2:3], v[4:5], 0, s[12:13]
	s_mov_b32 m0, s58
	s_addc_u32 s19, s31, 0
	global_load_lds_dwordx4 v[2:3], off
	s_add_i32 m0, s27, 0x1c000
	v_lshl_add_u64 v[2:3], s[18:19], 0, v[134:135]
	global_load_lds_dwordx4 v[2:3], off
	v_lshl_add_u64 v[2:3], s[18:19], 0, v[130:131]
	s_add_i32 m0, s27, 0x1e000
	s_sext_i32_i8 s63, s2
	global_load_lds_dwordx4 v[2:3], off
	v_and_b32_e32 v2, 15, v0
	v_lshlrev_b32_e32 v3, 1, v13
	v_lshlrev_b32_e32 v4, 2, v0
	v_lshlrev_b32_e32 v5, 6, v0
	s_movk_i32 s2, 0x3c0
	v_lshl_or_b32 v1, s16, 6, v2
	v_lshl_or_b32 v2, v2, 6, v3
	v_and_b32_e32 v4, 32, v4
	v_and_or_b32 v3, v5, s2, v3
	v_bitop3_b32 v154, s21, v3, v4 bitop3:0xf6
	v_lshlrev_b32_e32 v3, 9, v0
	v_bitop3_b32 v2, v2, s17, v4 bitop3:0xde
	v_and_b32_e32 v3, 0x30000, v3
	v_lshlrev_b32_e32 v4, 12, v14
	v_or3_b32 v3, v11, v3, v4
	v_add_u32_e32 v138, v3, v12
	v_lshlrev_b32_e32 v3, 5, v10
	s_waitcnt vmcnt(8)
	s_barrier
	s_waitcnt vmcnt(6)
	s_cmpk_lt_u32 s3, 0x100
	v_and_b32_e32 v3, 0x70000, v3
	s_cselect_b64 s[16:17], -1, 0
	v_or3_b32 v3, v11, v3, v4
	s_add_i32 s60, 0, 0x10000
	s_add_i32 s61, 0, 0x14000
	s_ashr_i32 s59, s15, 31
	v_or_b32_e32 v155, s20, v13
	v_mov_b32_e32 v139, v135
	v_add_u32_e32 v140, v3, v12
	v_mov_b32_e32 v141, v135
	v_mov_b64_e32 v[142:143], 0x600
	v_mov_b64_e32 v[144:145], 0x5ff
	v_add_u32_e32 v156, s60, v154
	v_add_u32_e32 v157, s61, v154
	v_add_u32_e32 v158, 0, v2
	s_movk_i32 s62, 0x1800
	s_barrier
	s_branch .LBB0_117

; #define PG8_STAGE(bufoff, gbase, voff) do { _Pragma("unroll") for (int _i = 0; _i < 2; ++_i) \
;         __builtin_amdgcn_global_load_lds((const unsigned*)((const char*)(gbase) + (voff)[_i]), (PG8_LAS unsigned*)(lds + (bufoff) + ldsw + _i * 8192), 16, 0, 0); } while (0)
; #define PG8_WAIT_V(n) asm volatile("s_waitcnt vmcnt(" #n ")" ::: "memory")
; #define PG8_BAR __builtin_amdgcn_s_barrier()
; template <class Epi, class Sched, bool ALIGN_EPI = false, bool SP2 = false, bool KSEG = false>
; __device__ __forceinline__ void gemm_phase(PG8_LAS unsigned char* lds, const Gemm g, const Sched& S, const Epi& E) {
;     ...
;     for (int i = 0; i < 2; ++i) { int R, C; stage_rc(tid * 16 + i * 8192, R, C); const int Rb = Epi::PERM ? ((R & ~31) + perm32(R & 31)) : R;
;         voffA[i] = (unsigned)(R * K + C) * 2u; voffB[i] = (unsigned)(Rb * K + C) * 2u; }
;     const size_t kstep = (size_t)(BK * 2);
;     const size_t hstep = (size_t)HALF * K * 2;
;     const size_t tstep = 2 * hstep;
;     const unsigned ldsw = (unsigned)wid * 1024u;
;     const int aoff = lds_byte(wr * 64 + fr, fq * 8), boff = lds_byte(wc * 32 + fr, fq * 8);
;     ...
;         PG8_STAGE(PG8_SB(0, 0), cB, voffB); PG8_STAGE(PG8_SB(0, 1), cB + hstep, voffB); PG8_STAGE(PG8_SA(0, 0), cA, voffA); PG8_STAGE(PG8_SA(0, 1), cA + hstep, voffA);
;         if (wr == 1) PG8_BAR;
;         PG8_WAIT_V(2); PG8_BAR;
;         PG8_STAGE(PG8_SB(1, 0), cB + kstep, voffB); PG8_STAGE(PG8_SA(1, 0), cA + kstep, voffA); PG8_STAGE(PG8_SB(1, 1), cB + hstep + kstep, voffB);
;         PG8_WAIT_V(6); PG8_BAR;
.LBB0_403:
	s_lshl_b32 s3, s3, 5
	s_mov_b64 s[8:9], 0x80
	s_and_b32 s20, s3, 0x60
	s_add_i32 m0, s51, 0x18000
	v_lshl_add_u64 v[10:11], v[10:11], 0, s[8:9]
	s_lshl_b32 s11, s2, 13
	s_lshl_b32 s3, s20, 7
	global_load_lds_dwordx4 v[10:11], off
	v_lshl_add_u64 v[8:9], v[8:9], 0, s[8:9]
	s_add_i32 m0, s51, 0x1a000
	s_add_i32 s55, s51, 0x8000
	s_add_i32 s56, s51, 0xa000
	global_load_lds_dwordx4 v[8:9], off
	v_lshl_add_u64 v[4:5], v[4:5], 0, s[8:9]
	s_mov_b32 m0, s55
	s_add_u32 s4, s42, 0x80080
	global_load_lds_dwordx4 v[4:5], off
	v_lshl_add_u64 v[4:5], v[6:7], 0, s[8:9]
	s_mov_b32 m0, s56
	s_addc_u32 s5, s43, 0
	global_load_lds_dwordx4 v[4:5], off
	s_add_i32 m0, s51, 0x1c000
	v_lshl_add_u64 v[4:5], s[4:5], 0, v[136:137]
	global_load_lds_dwordx4 v[4:5], off
	v_lshl_add_u64 v[4:5], s[4:5], 0, v[140:141]
	s_add_i32 m0, s51, 0x1e000
	v_lshlrev_b32_e32 v7, 2, v0
	global_load_lds_dwordx4 v[4:5], off
	v_bfe_u32 v5, v0, 4, 2
	v_and_b32_e32 v4, 15, v0
	v_lshlrev_b32_e32 v6, 4, v5
	v_lshl_or_b32 v1, s2, 6, v4
	v_lshl_or_b32 v4, v4, 6, v6
	v_and_b32_e32 v7, 32, v7
	v_bitop3_b32 v8, v4, s11, v7 bitop3:0xde
	v_lshlrev_b32_e32 v4, 6, v0
	s_movk_i32 s2, 0x3c0
	v_and_or_b32 v4, v4, s2, v6
	v_bitop3_b32 v157, s3, v4, v7 bitop3:0xf6
	v_lshlrev_b32_e32 v4, 9, v0
	v_and_b32_e32 v4, 0x30000, v4
	v_lshlrev_b32_e32 v6, 12, v13
	v_or3_b32 v4, v3, v4, v6
	s_mov_b64 s[4:5], 0x80080
	v_cmp_eq_u32_e64 s[2:3], 0, v5
	v_lshl_or_b32 v159, v5, 3, s20
	v_add_u32_e32 v4, v4, v12
	v_mov_b32_e32 v5, v2
	v_lshl_add_u64 v[142:143], v[4:5], 0, s[4:5]
	v_lshlrev_b32_e32 v4, 5, v14
	v_and_b32_e32 v4, 0x70000, v4
	s_waitcnt vmcnt(8)
	s_barrier
	s_waitcnt vmcnt(6)
	s_cmpk_lt_u32 s10, 0x100
	v_or3_b32 v3, v3, v4, v6
	s_cselect_b64 s[10:11], -1, 0
	v_add_u32_e32 v4, v3, v12
	s_add_i32 s65, 0, 0x10000
	s_add_i32 s66, 0, 0x14000
	v_lshlrev_b32_e32 v158, 4, v1
	v_lshl_add_u64 v[144:145], v[4:5], 0, s[4:5]
	v_mov_b64_e32 v[146:147], 0x400
	v_mov_b64_e32 v[148:149], 0x3ff
	s_add_i32 s57, 0, 0x20000
	s_add_i32 s58, 0, 0x20100
	s_add_i32 s59, 0, 0x20200
	s_add_i32 s60, 0, 0x20300
	s_add_i32 s61, 0, 0x20800
	s_add_i32 s62, 0, 0x20900
	s_add_i32 s63, 0, 0x20a00
	s_add_i32 s64, 0, 0x20b00
	v_add_u32_e32 v160, s65, v157
	v_add_u32_e32 v161, s66, v157
	v_add_u32_e32 v162, 0, v8
	s_movk_i32 s67, 0x3fff
	s_movk_i32 s80, 0x3f7f
	s_movk_i32 s81, 0x3f6f
	s_movk_i32 s82, 0x3f5f
	s_movk_i32 s83, 0x3f4f
	s_barrier
	s_branch .LBB0_406

; #define PG8_STAGE(bufoff, gbase, voff) do { _Pragma("unroll") for (int _i = 0; _i < 2; ++_i) \
;         __builtin_amdgcn_global_load_lds((const unsigned*)((const char*)(gbase) + (voff)[_i]), (PG8_LAS unsigned*)(lds + (bufoff) + ldsw + _i * 8192), 16, 0, 0); } while (0)
; #define PG8_WAIT_V(n) asm volatile("s_waitcnt vmcnt(" #n ")" ::: "memory")
; #define PG8_BAR __builtin_amdgcn_s_barrier()
; template <class Epi, class Sched, bool ALIGN_EPI = false, bool SP2 = false, bool KSEG = false>
; __device__ __forceinline__ void gemm_phase(PG8_LAS unsigned char* lds, const Gemm g, const Sched& S, const Epi& E) {
;     ...
;     for (int i = 0; i < 2; ++i) { int R, C; stage_rc(tid * 16 + i * 8192, R, C); const int Rb = Epi::PERM ? ((R & ~31) + perm32(R & 31)) : R;
;         voffA[i] = (unsigned)(R * K + C) * 2u; voffB[i] = (unsigned)(Rb * K + C) * 2u; }
;     const size_t kstep = (size_t)(BK * 2);
;     const size_t hstep = (size_t)HALF * K * 2;
;     const size_t tstep = 2 * hstep;
;     const unsigned ldsw = (unsigned)wid * 1024u;
;     const int aoff = lds_byte(wr * 64 + fr, fq * 8), boff = lds_byte(wc * 32 + fr, fq * 8);
;     ...
;         PG8_STAGE(PG8_SB(0, 0), cB, voffB); PG8_STAGE(PG8_SB(0, 1), cB + hstep, voffB); PG8_STAGE(PG8_SA(0, 0), cA, voffA); PG8_STAGE(PG8_SA(0, 1), cA + hstep, voffA);
;         if (wr == 1) PG8_BAR;
;         PG8_WAIT_V(2); PG8_BAR;
;         PG8_STAGE(PG8_SB(1, 0), cB + kstep, voffB); PG8_STAGE(PG8_SA(1, 0), cA + kstep, voffA); PG8_STAGE(PG8_SB(1, 1), cB + hstep + kstep, voffB);
;         PG8_WAIT_V(6); PG8_BAR;
.LBB0_491:
	s_lshl_b32 s10, s10, 5
	s_and_b32 s24, s10, 0x60
	s_mov_b64 s[10:11], 0x80
	s_add_i32 m0, s31, 0x18000
	v_lshl_add_u64 v[2:3], v[2:3], 0, s[10:11]
	s_lshl_b32 s13, s12, 13
	global_load_lds_dwordx4 v[2:3], off
	v_lshl_add_u64 v[2:3], v[4:5], 0, s[10:11]
	s_add_i32 m0, s31, 0x1a000
	s_add_i32 s52, s31, 0x8000
	s_add_i32 s53, s31, 0xa000
	global_load_lds_dwordx4 v[2:3], off
	v_lshl_add_u64 v[2:3], v[8:9], 0, s[10:11]
	s_mov_b32 m0, s52
	s_add_u32 s22, s38, 0x80080
	global_load_lds_dwordx4 v[2:3], off
	v_lshl_add_u64 v[2:3], v[6:7], 0, s[10:11]
	s_mov_b32 m0, s53
	s_addc_u32 s23, s39, 0
	global_load_lds_dwordx4 v[2:3], off
	s_add_i32 m0, s31, 0x1c000
	v_lshl_add_u64 v[2:3], s[22:23], 0, v[134:135]
	global_load_lds_dwordx4 v[2:3], off
	v_lshl_add_u64 v[2:3], s[22:23], 0, v[138:139]
	s_add_i32 m0, s31, 0x1e000
	v_lshlrev_b32_e32 v4, 12, v160
	global_load_lds_dwordx4 v[2:3], off
	v_lshlrev_b32_e32 v3, 2, v159
	v_lshl_or_b32 v2, v159, 6, v163
	v_and_b32_e32 v3, 32, v3
	v_bitop3_b32 v2, v2, s13, v3 bitop3:0xde
	v_lshlrev_b32_e32 v3, 9, v0
	v_and_b32_e32 v3, 0x30000, v3
	v_or3_b32 v3, v1, v3, v4
	v_add_u32_e32 v140, v3, v158
	v_lshlrev_b32_e32 v3, 5, v161
	s_waitcnt vmcnt(8)
	s_barrier
	s_waitcnt vmcnt(6)
	s_cmpk_lt_u32 s5, 0x100
	v_and_b32_e32 v3, 0x70000, v3
	v_lshl_or_b32 v165, s12, 6, v159
	v_lshl_or_b32 v166, s24, 7, v164
	s_cselect_b64 s[12:13], -1, 0
	v_mov_b32_e32 v141, 0
	v_or3_b32 v3, v1, v3, v4
	s_add_i32 s54, 0, 0x10000
	s_add_i32 s55, 0, 0x14000
	s_sext_i32_i16 s57, s4
	v_or_b32_e32 v167, s24, v162
	v_add_u32_e32 v142, v3, v158
	v_mov_b32_e32 v143, v141
	v_mov_b64_e32 v[144:145], 0xb00
	v_mov_b64_e32 v[146:147], 0xaff
	v_add_u32_e32 v168, s54, v166
	v_add_u32_e32 v169, s55, v166
	v_add_u32_e32 v170, 0, v2
	v_mov_b32_e32 v171, 0x358637bd
	s_movk_i32 s56, 0x2c00
	s_barrier
	s_branch .LBB0_494

; #define PG8_STAGE(bufoff, gbase, voff) do { _Pragma("unroll") for (int _i = 0; _i < 2; ++_i) \
;         __builtin_amdgcn_global_load_lds((const unsigned*)((const char*)(gbase) + (voff)[_i]), (PG8_LAS unsigned*)(lds + (bufoff) + ldsw + _i * 8192), 16, 0, 0); } while (0)
; #define PG8_WAIT_V(n) asm volatile("s_waitcnt vmcnt(" #n ")" ::: "memory")
; #define PG8_BAR __builtin_amdgcn_s_barrier()
; template <class Epi, class Sched, bool ALIGN_EPI = false, bool SP2 = false, bool KSEG = false>
; __device__ __forceinline__ void gemm_phase(PG8_LAS unsigned char* lds, const Gemm g, const Sched& S, const Epi& E) {
;     ...
;     for (int i = 0; i < 2; ++i) { int R, C; stage_rc(tid * 16 + i * 8192, R, C); const int Rb = Epi::PERM ? ((R & ~31) + perm32(R & 31)) : R;
;         voffA[i] = (unsigned)(R * K + C) * 2u; voffB[i] = (unsigned)(Rb * K + C) * 2u; }
;     const size_t kstep = (size_t)(BK * 2);
;     const size_t hstep = (size_t)HALF * K * 2;
;     const size_t tstep = 2 * hstep;
;     const unsigned ldsw = (unsigned)wid * 1024u;
;     const int aoff = lds_byte(wr * 64 + fr, fq * 8), boff = lds_byte(wc * 32 + fr, fq * 8);
;     ...
;         PG8_STAGE(PG8_SB(0, 0), cB, voffB); PG8_STAGE(PG8_SB(0, 1), cB + hstep, voffB); PG8_STAGE(PG8_SA(0, 0), cA, voffA); PG8_STAGE(PG8_SA(0, 1), cA + hstep, voffA);
;         if (wr == 1) PG8_BAR;
;         PG8_WAIT_V(2); PG8_BAR;
;         PG8_STAGE(PG8_SB(1, 0), cB + kstep, voffB); PG8_STAGE(PG8_SA(1, 0), cA + kstep, voffA); PG8_STAGE(PG8_SB(1, 1), cB + hstep + kstep, voffB);
;         PG8_WAIT_V(6); PG8_BAR;
.LBB0_523:
	s_mov_b64 s[26:27], 0x80
	s_lshl_b32 s12, s12, 5
	s_add_i32 m0, s44, 0x18000
	v_lshl_add_u64 v[2:3], v[2:3], 0, s[26:27]
	s_lshl_b32 s28, s11, 13
	s_and_b32 s30, s12, 0x60
	global_load_lds_dwordx4 v[2:3], off
	v_lshl_add_u64 v[2:3], v[4:5], 0, s[26:27]
	s_add_i32 m0, s44, 0x1a000
	s_add_i32 s54, s44, 0x8000
	s_add_i32 s55, s44, 0xa000
	global_load_lds_dwordx4 v[2:3], off
	v_lshl_add_u64 v[2:3], v[8:9], 0, s[26:27]
	s_mov_b32 m0, s54
	s_add_u32 s12, s38, 0x160080
	global_load_lds_dwordx4 v[2:3], off
	v_lshl_add_u64 v[2:3], v[6:7], 0, s[26:27]
	s_mov_b32 m0, s55
	s_addc_u32 s13, s39, 0
	global_load_lds_dwordx4 v[2:3], off
	s_add_i32 m0, s44, 0x1c000
	v_lshl_add_u64 v[2:3], s[12:13], 0, v[130:131]
	global_load_lds_dwordx4 v[2:3], off
	v_lshl_add_u64 v[2:3], s[12:13], 0, v[144:145]
	s_add_i32 m0, s44, 0x1e000
	s_cmpk_lt_u32 s10, 0x100
	global_load_lds_dwordx4 v[2:3], off
	v_lshlrev_b32_e32 v3, 2, v159
	v_lshl_or_b32 v2, v159, 6, v169
	v_and_b32_e32 v3, 32, v3
	v_bitop3_b32 v2, v2, s28, v3 bitop3:0xde
	s_waitcnt vmcnt(8)
	s_barrier
	s_waitcnt vmcnt(6)
	v_add_u16_e32 v3, v1, v158
	v_lshl_or_b32 v171, s30, 7, v168
	s_cselect_b64 s[28:29], -1, 0
	v_lshrrev_b16_e32 v3, 1, v3
	v_mov_b32_e32 v147, 0
	s_add_i32 s56, 0, 0x10000
	s_add_i32 s57, 0, 0x14000
	v_lshl_or_b32 v170, s11, 6, v159
	v_or_b32_e32 v172, s30, v167
	v_add_lshl_u32 v146, v165, v3, 1
	v_add_lshl_u32 v148, v166, v3, 1
	v_mov_b32_e32 v149, v147
	v_mov_b64_e32 v[150:151], 0x200
	v_mov_b64_e32 v[152:153], 0x1ff
	v_add_u32_e32 v173, s56, v171
	v_add_u32_e32 v174, s57, v171
	v_add_u32_e32 v175, 0, v2
	s_barrier
	s_branch .LBB0_526

; #define PG8_STAGE(bufoff, gbase, voff) do { _Pragma("unroll") for (int _i = 0; _i < 2; ++_i) \
;         __builtin_amdgcn_global_load_lds((const unsigned*)((const char*)(gbase) + (voff)[_i]), (PG8_LAS unsigned*)(lds + (bufoff) + ldsw + _i * 8192), 16, 0, 0); } while (0)
; #define PG8_WAIT_V(n) asm volatile("s_waitcnt vmcnt(" #n ")" ::: "memory")
; #define PG8_BAR __builtin_amdgcn_s_barrier()
; template <class Epi, class Sched, bool ALIGN_EPI = false, bool SP2 = false, bool KSEG = false>
; __device__ __forceinline__ void gemm_phase(PG8_LAS unsigned char* lds, const Gemm g, const Sched& S, const Epi& E) {
;     ...
;     for (int i = 0; i < 2; ++i) { int R, C; stage_rc(tid * 16 + i * 8192, R, C); const int Rb = Epi::PERM ? ((R & ~31) + perm32(R & 31)) : R;
;         voffA[i] = (unsigned)(R * K + C) * 2u; voffB[i] = (unsigned)(Rb * K + C) * 2u; }
;     const size_t kstep = (size_t)(BK * 2);
;     const size_t hstep = (size_t)HALF * K * 2;
;     const size_t tstep = 2 * hstep;
;     const unsigned ldsw = (unsigned)wid * 1024u;
;     const int aoff = lds_byte(wr * 64 + fr, fq * 8), boff = lds_byte(wc * 32 + fr, fq * 8);
;     ...
;         PG8_STAGE(PG8_SB(0, 0), cB, voffB); PG8_STAGE(PG8_SB(0, 1), cB + hstep, voffB); PG8_STAGE(PG8_SA(0, 0), cA, voffA); PG8_STAGE(PG8_SA(0, 1), cA + hstep, voffA);
;         if (wr == 1) PG8_BAR;
;         PG8_WAIT_V(2); PG8_BAR;
;         PG8_STAGE(PG8_SB(1, 0), cB + kstep, voffB); PG8_STAGE(PG8_SA(1, 0), cA + kstep, voffA); PG8_STAGE(PG8_SB(1, 1), cB + hstep + kstep, voffB);
;         PG8_WAIT_V(6); PG8_BAR;
.LBB0_575:
	s_lshl_b32 s12, s12, 5
	s_and_b32 s28, s12, 0x60
	s_mov_b64 s[12:13], 0x80
	s_add_i32 m0, s55, 0x18000
	v_lshl_add_u64 v[2:3], v[2:3], 0, s[12:13]
	s_lshl_b32 s25, s24, 13
	global_load_lds_dwordx4 v[2:3], off
	v_lshl_add_u64 v[2:3], v[4:5], 0, s[12:13]
	s_add_i32 m0, s55, 0x1a000
	s_add_i32 s60, s55, 0x8000
	s_add_i32 s61, s55, 0xa000
	global_load_lds_dwordx4 v[2:3], off
	v_lshl_add_u64 v[2:3], v[8:9], 0, s[12:13]
	s_mov_b32 m0, s60
	s_add_u32 s26, s42, 0x80080
	global_load_lds_dwordx4 v[2:3], off
	v_lshl_add_u64 v[2:3], v[6:7], 0, s[12:13]
	s_mov_b32 m0, s61
	s_addc_u32 s27, s43, 0
	global_load_lds_dwordx4 v[2:3], off
	s_add_i32 m0, s55, 0x1c000
	v_lshl_add_u64 v[2:3], s[26:27], 0, v[134:135]
	global_load_lds_dwordx4 v[2:3], off
	v_lshl_add_u64 v[2:3], s[26:27], 0, v[138:139]
	s_add_i32 m0, s55, 0x1e000
	v_lshlrev_b32_e32 v4, 12, v160
	global_load_lds_dwordx4 v[2:3], off
	v_lshlrev_b32_e32 v3, 2, v159
	v_lshl_or_b32 v2, v159, 6, v163
	v_and_b32_e32 v3, 32, v3
	v_bitop3_b32 v2, v2, s25, v3 bitop3:0xde
	v_lshlrev_b32_e32 v3, 9, v0
	v_and_b32_e32 v3, 0x30000, v3
	v_or3_b32 v3, v1, v3, v4
	v_add_u32_e32 v146, v3, v158
	v_lshlrev_b32_e32 v3, 5, v161
	s_waitcnt vmcnt(8)
	s_barrier
	s_waitcnt vmcnt(6)
	s_cmpk_lt_u32 s7, 0x100
	v_and_b32_e32 v3, 0x70000, v3
	v_lshl_or_b32 v170, s24, 6, v159
	v_lshl_or_b32 v163, s28, 7, v164
	s_cselect_b64 s[24:25], -1, 0
	v_mov_b32_e32 v147, 0
	v_or3_b32 v3, v1, v3, v4
	s_add_i32 s62, 0, 0x10000
	s_add_i32 s63, 0, 0x14000
	s_sext_i32_i16 s39, s6
	v_or_b32_e32 v162, s28, v162
	v_add_u32_e32 v148, v3, v158
	v_mov_b32_e32 v149, v147
	v_mov_b64_e32 v[150:151], 0xb00
	v_mov_b64_e32 v[152:153], 0xaff
	v_add_u32_e32 v160, s62, v163
	v_add_u32_e32 v161, s63, v163
	v_add_u32_e32 v164, 0, v2
	v_mov_b32_e32 v171, 0x358637bd
	s_movk_i32 s64, 0x2c00
	s_barrier
	s_branch .LBB0_578

; #define PG8_STAGE(bufoff, gbase, voff) do { _Pragma("unroll") for (int _i = 0; _i < 2; ++_i) \
;         __builtin_amdgcn_global_load_lds((const unsigned*)((const char*)(gbase) + (voff)[_i]), (PG8_LAS unsigned*)(lds + (bufoff) + ldsw + _i * 8192), 16, 0, 0); } while (0)
; #define PG8_WAIT_V(n) asm volatile("s_waitcnt vmcnt(" #n ")" ::: "memory")
; #define PG8_BAR __builtin_amdgcn_s_barrier()
; template <class Epi, class Sched, bool ALIGN_EPI = false, bool SP2 = false, bool KSEG = false>
; __device__ __forceinline__ void gemm_phase(PG8_LAS unsigned char* lds, const Gemm g, const Sched& S, const Epi& E) {
;     ...
;     for (int i = 0; i < 2; ++i) { int R, C; stage_rc(tid * 16 + i * 8192, R, C); const int Rb = Epi::PERM ? ((R & ~31) + perm32(R & 31)) : R;
;         voffA[i] = (unsigned)(R * K + C) * 2u; voffB[i] = (unsigned)(Rb * K + C) * 2u; }
;     const size_t kstep = (size_t)(BK * 2);
;     const size_t hstep = (size_t)HALF * K * 2;
;     const size_t tstep = 2 * hstep;
;     const unsigned ldsw = (unsigned)wid * 1024u;
;     const int aoff = lds_byte(wr * 64 + fr, fq * 8), boff = lds_byte(wc * 32 + fr, fq * 8);
;     ...
;         PG8_STAGE(PG8_SB(0, 0), cB, voffB); PG8_STAGE(PG8_SB(0, 1), cB + hstep, voffB); PG8_STAGE(PG8_SA(0, 0), cA, voffA); PG8_STAGE(PG8_SA(0, 1), cA + hstep, voffA);
;         if (wr == 1) PG8_BAR;
;         PG8_WAIT_V(2); PG8_BAR;
;         PG8_STAGE(PG8_SB(1, 0), cB + kstep, voffB); PG8_STAGE(PG8_SA(1, 0), cA + kstep, voffA); PG8_STAGE(PG8_SB(1, 1), cB + hstep + kstep, voffB);
;         PG8_WAIT_V(6); PG8_BAR;
.LBB0_607:
	s_mov_b64 s[12:13], 0x80
	s_lshl_b32 s8, s8, 5
	s_add_i32 m0, s31, 0x18000
	v_lshl_add_u64 v[2:3], v[2:3], 0, s[12:13]
	s_lshl_b32 s18, s7, 13
	s_and_b32 s20, s8, 0x60
	global_load_lds_dwordx4 v[2:3], off
	v_lshl_add_u64 v[2:3], v[4:5], 0, s[12:13]
	s_add_i32 m0, s31, 0x1a000
	s_add_i32 s40, s31, 0x8000
	s_add_i32 s41, s31, 0xa000
	global_load_lds_dwordx4 v[2:3], off
	v_lshl_add_u64 v[2:3], v[8:9], 0, s[12:13]
	s_mov_b32 m0, s40
	s_add_u32 s8, s26, 0x160080
	global_load_lds_dwordx4 v[2:3], off
	v_lshl_add_u64 v[2:3], v[6:7], 0, s[12:13]
	s_mov_b32 m0, s41
	s_addc_u32 s9, s27, 0
	global_load_lds_dwordx4 v[2:3], off
	s_add_i32 m0, s31, 0x1c000
	v_lshl_add_u64 v[2:3], s[8:9], 0, v[130:131]
	global_load_lds_dwordx4 v[2:3], off
	v_lshl_add_u64 v[2:3], s[8:9], 0, v[144:145]
	s_add_i32 m0, s31, 0x1e000
	v_lshlrev_b32_e32 v4, 2, v159
	global_load_lds_dwordx4 v[2:3], off
	v_lshl_or_b32 v3, v159, 6, v169
	v_and_b32_e32 v4, 32, v4
	s_waitcnt vmcnt(8)
	s_barrier
	s_waitcnt vmcnt(6)
	s_cmpk_lt_u32 s6, 0x100
	v_add_u16_e32 v1, v1, v158
	v_lshl_or_b32 v2, s7, 6, v159
	v_bitop3_b32 v3, v3, s18, v4 bitop3:0xde
	v_lshl_or_b32 v150, s20, 7, v168
	s_cselect_b64 s[18:19], -1, 0
	v_lshrrev_b16_e32 v1, 1, v1
	v_mov_b32_e32 v133, 0
	s_add_i32 s42, 0, 0x10000
	s_add_i32 s43, 0, 0x14000
	v_add_u32_e32 v151, 0x4000, v2
	v_or_b32_e32 v152, s20, v167
	v_add_lshl_u32 v132, v165, v1, 1
	v_add_lshl_u32 v134, v166, v1, 1
	v_mov_b32_e32 v135, v133
	v_mov_b64_e32 v[136:137], 0x200
	v_mov_b64_e32 v[138:139], 0x1ff
	v_add_u32_e32 v1, s42, v150
	v_add_u32_e32 v153, s43, v150
	v_add_u32_e32 v154, 0, v3
	s_barrier
	s_branch .LBB0_610
